# baseline (speedup 1.0000x reference)
; __device__ __forceinline__ unsigned cvt_pk_bf16(float lo, float hi) { unsigned r; asm volatile("v_cvt_pk_bf16_f32 %0, %1, %2" : "=v"(r) : "v"(lo), "v"(hi)); return r; }
;     __device__ __forceinline__ void operator()(const f32x4 (&acc)[2][2][4][2], const Unit& u, int wr, int wc, int fr, int fq) const {
;         const int col0 = u.pn * BM + wc * 32 + 4 * fq;
; #pragma unroll
;         for (int ai = 0; ai < 2; ++ai)
; #pragma unroll
;             for (int m = 0; m < 4; ++m) { const int row = u.pm * BM + ai * HALF + wr * 64 + m * 16 + fr;
;                 const float* b = (row < HALF_TOK) ? base0 + (size_t)row * DM : base1 + (size_t)(row - HALF_TOK) * DM;
;                 float* o = out + (size_t)(row & omask) * DM; float sq = 0.f;
; #pragma unroll
;                 for (int bj = 0; bj < 2; ++bj)
; #pragma unroll
;                     for (int n = 0; n < 2; ++n) { const int c = col0 + bj * HALF + n * 16; const f32x4 bs = *(const f32x4*)(b + c); const f32x4 v = bs + acc[ai][bj][m][n]; *(f32x4*)(o + c) = v;
;                         if (xb) { sq += (v[0] * v[0] + v[1] * v[1]) + (v[2] * v[2] + v[3] * v[3]); *(u32x2*)(xb + (size_t)row * DM + c) = (u32x2){cvt_pk_bf16(v[0], v[1]), cvt_pk_bf16(v[2], v[3])}; } }
;                 if (xb) { sq += __shfl_xor(sq, 16); sq += __shfl_xor(sq, 32); if (fq == 0) ssq[(size_t)row * 32 + u.pn * 4 + wc] = sq; }
.LBB0_78:
	s_lshl_b32 s4, s25, 8
	s_cmp_gt_u32 s4, s75
	s_cselect_b32 s44, s16, s14
	s_cselect_b32 s45, s17, s15
	s_cselect_b32 s5, 0x2000, 0
	s_sub_u32 s5, s4, s5
	s_lshl_b32 s5, s5, 13
	s_add_u32 s44, s44, s5
	s_addc_u32 s45, s45, 0
	s_and_b32 s5, s4, s34
	s_lshl_b32 s5, s5, 13
	s_add_u32 s46, s38, s5
	s_addc_u32 s47, s39, 0
	s_lshl_b32 s5, s4, 12
	s_add_u32 s48, s18, s5
	s_addc_u32 s49, s19, 0
	s_lshl_b32 s5, s4, 7
	s_add_u32 s66, s20, s5
	s_addc_u32 s67, s21, 0
	s_lshl_b32 s5, s0, 4
	s_add_u32 s66, s66, s5
	s_addc_u32 s67, s67, 0
	s_lshl_b32 s5, s35, 2
	s_add_u32 s66, s66, s5
	s_addc_u32 s67, s67, 0
	v_lshl_or_b32 v141, s0, 8, v154
	v_lshlrev_b32_e32 v142, 7, v152
	v_lshlrev_b32_e32 v140, 2, v141
	v_lshlrev_b32_e32 v141, 1, v141
	v_lshl_add_u32 v140, v152, 13, v140
	v_lshl_add_u32 v141, v152, 12, v141
	v_and_b32_e32 v143, 16, v190
	v_lshrrev_b32_e32 v143, 1, v143
	v_lshl_add_u32 v143, v143, 1, v143
	v_add_u32_e32 v143, v141, v143
	s_mov_b32 s4, s44
	s_mov_b32 s5, s45
	global_load_dwordx4 v[202:205], v140, s[4:5] offset:0
	global_load_dwordx4 v[206:209], v140, s[4:5] offset:64
	global_load_dwordx4 v[210:213], v140, s[4:5] offset:512
	global_load_dwordx4 v[214:217], v140, s[4:5] offset:576
	s_add_u32 s4, s44, 0x20000
	s_addc_u32 s5, s45, 0
	global_load_dwordx4 v[218:221], v140, s[4:5] offset:0
	global_load_dwordx4 v[222:225], v140, s[4:5] offset:64
	global_load_dwordx4 v[226:229], v140, s[4:5] offset:512
	global_load_dwordx4 v[230:233], v140, s[4:5] offset:576
	s_add_u32 s4, s44, 0x40000
	s_addc_u32 s5, s45, 0
	global_load_dwordx4 v[156:159], v140, s[4:5] offset:0
	global_load_dwordx4 v[160:163], v140, s[4:5] offset:64
	global_load_dwordx4 v[164:167], v140, s[4:5] offset:512
	global_load_dwordx4 v[168:171], v140, s[4:5] offset:576
	s_add_u32 s4, s44, 0x60000
	s_addc_u32 s5, s45, 0
	global_load_dwordx4 v[144:147], v140, s[4:5] offset:0
	global_load_dwordx4 v[148:151], v140, s[4:5] offset:64
	global_load_dwordx4 v[172:175], v140, s[4:5] offset:512
	global_load_dwordx4 v[176:179], v140, s[4:5] offset:576
	s_and_b64 vcc, exec, s[42:43]
	s_cbranch_vccz .Lepi_plain
	s_waitcnt vmcnt(12)
	v_pk_add_f32 v[124:125], v[124:125], v[202:203]
	v_pk_add_f32 v[126:127], v[126:127], v[204:205]
	v_pk_add_f32 v[120:121], v[120:121], v[206:207]
	v_pk_add_f32 v[122:123], v[122:123], v[208:209]
	v_pk_add_f32 v[116:117], v[116:117], v[210:211]
	v_pk_add_f32 v[118:119], v[118:119], v[212:213]
	v_pk_add_f32 v[112:113], v[112:113], v[214:215]
	v_pk_add_f32 v[114:115], v[114:115], v[216:217]
	s_mov_b32 s4, s46
	s_mov_b32 s5, s47
	global_store_dwordx4 v140, v[124:127], s[4:5] offset:0
	global_store_dwordx4 v140, v[120:123], s[4:5] offset:64
	global_store_dwordx4 v140, v[116:119], s[4:5] offset:512
	global_store_dwordx4 v140, v[112:115], s[4:5] offset:576
	s_mov_b32 s4, s48
	s_mov_b32 s5, s49
	v_cvt_pk_bf16_f32 v236, v124, v125
	v_cvt_pk_bf16_f32 v237, v126, v127
	v_cvt_pk_bf16_f32 v238, v120, v121
	v_cvt_pk_bf16_f32 v239, v122, v123
	v_mul_f32_e32 v182, v125, v125
	v_mul_f32_e32 v183, v127, v127
	v_fmac_f32_e32 v182, v124, v124
	v_fmac_f32_e32 v183, v126, v126
	v_add_f32_e32 v234, v182, v183
	v_mul_f32_e32 v182, v121, v121
	v_mul_f32_e32 v183, v123, v123
	v_fmac_f32_e32 v182, v120, v120
	v_fmac_f32_e32 v183, v122, v122
	v_add_f32_e32 v182, v182, v183
	v_add_f32_e32 v234, v234, v182
	v_permlane16_swap_b32_e32 v236, v238
	v_permlane16_swap_b32_e32 v237, v239
	global_store_dwordx4 v143, v[236:239], s[4:5] offset:0
	s_nop 1
	v_cvt_pk_bf16_f32 v236, v116, v117
	v_cvt_pk_bf16_f32 v237, v118, v119
	v_cvt_pk_bf16_f32 v238, v112, v113
	v_cvt_pk_bf16_f32 v239, v114, v115
	v_mul_f32_e32 v182, v117, v117
	v_mul_f32_e32 v183, v119, v119
	v_fmac_f32_e32 v182, v116, v116
	v_fmac_f32_e32 v183, v118, v118
	v_add_f32_e32 v182, v182, v183
	v_add_f32_e32 v234, v234, v182
	v_mul_f32_e32 v182, v113, v113
	v_mul_f32_e32 v183, v115, v115
	v_fmac_f32_e32 v182, v112, v112
	v_fmac_f32_e32 v183, v114, v114
	v_add_f32_e32 v182, v182, v183
	v_add_f32_e32 v234, v234, v182
	v_permlane16_swap_b32_e32 v236, v238
	v_permlane16_swap_b32_e32 v237, v239
	global_store_dwordx4 v143, v[236:239], s[4:5] offset:256
	v_mov_b32_e32 v235, v234
	s_nop 1
	v_permlane16_swap_b32_e32 v234, v235
	v_add_f32_e32 v234, v234, v235
	v_mov_b32_e32 v235, v234
	s_nop 1
	v_permlane32_swap_b32_e32 v234, v235
	v_add_f32_e32 v234, v234, v235
	s_mov_b32 s4, s66
	s_mov_b32 s5, s67
	s_and_saveexec_b64 s[10:11], s[6:7]
	global_store_dword v142, v234, s[4:5]
	s_mov_b64 exec, s[10:11]
	s_add_u32 s4, s44, 0x100000
	s_addc_u32 s5, s45, 0
	global_load_dwordx4 v[202:205], v140, s[4:5] offset:0
	global_load_dwordx4 v[206:209], v140, s[4:5] offset:64
	global_load_dwordx4 v[210:213], v140, s[4:5] offset:512
	global_load_dwordx4 v[214:217], v140, s[4:5] offset:576
	s_waitcnt vmcnt(19)
; __device__ __forceinline__ unsigned cvt_pk_bf16(float lo, float hi) { unsigned r; asm volatile("v_cvt_pk_bf16_f32 %0, %1, %2" : "=v"(r) : "v"(lo), "v"(hi)); return r; }
;     __device__ __forceinline__ void operator()(const f32x4 (&acc)[2][2][4][2], const Unit& u, int wr, int wc, int fr, int fq) const {
;     ...
;             for (int m = 0; m < 4; ++m) { const int row = u.pm * BM + ai * HALF + wr * 64 + m * 16 + fr;
;                 const float* b = (row < HALF_TOK) ? base0 + (size_t)row * DM : base1 + (size_t)(row - HALF_TOK) * DM;
;                 float* o = out + (size_t)(row & omask) * DM; float sq = 0.f;
; #pragma unroll
;                 for (int bj = 0; bj < 2; ++bj)
; #pragma unroll
;                     for (int n = 0; n < 2; ++n) { const int c = col0 + bj * HALF + n * 16; const f32x4 bs = *(const f32x4*)(b + c); const f32x4 v = bs + acc[ai][bj][m][n]; *(f32x4*)(o + c) = v;
;                         if (xb) { sq += (v[0] * v[0] + v[1] * v[1]) + (v[2] * v[2] + v[3] * v[3]); *(u32x2*)(xb + (size_t)row * DM + c) = (u32x2){cvt_pk_bf16(v[0], v[1]), cvt_pk_bf16(v[2], v[3])}; } }
;                 if (xb) { sq += __shfl_xor(sq, 16); sq += __shfl_xor(sq, 32); if (fq == 0) ssq[(size_t)row * 32 + u.pn * 4 + wc] = sq; }
	v_pk_add_f32 v[108:109], v[108:109], v[218:219]
	v_pk_add_f32 v[110:111], v[110:111], v[220:221]
	v_pk_add_f32 v[104:105], v[104:105], v[222:223]
	v_pk_add_f32 v[106:107], v[106:107], v[224:225]
	v_pk_add_f32 v[100:101], v[100:101], v[226:227]
	v_pk_add_f32 v[102:103], v[102:103], v[228:229]
	v_pk_add_f32 v[96:97], v[96:97], v[230:231]
	v_pk_add_f32 v[98:99], v[98:99], v[232:233]
	s_add_u32 s4, s46, 0x20000
	s_addc_u32 s5, s47, 0
	global_store_dwordx4 v140, v[108:111], s[4:5] offset:0
	global_store_dwordx4 v140, v[104:107], s[4:5] offset:64
	global_store_dwordx4 v140, v[100:103], s[4:5] offset:512
	global_store_dwordx4 v140, v[96:99], s[4:5] offset:576
	s_add_u32 s4, s48, 0x10000
	s_addc_u32 s5, s49, 0
	v_cvt_pk_bf16_f32 v236, v108, v109
	v_cvt_pk_bf16_f32 v237, v110, v111
	v_cvt_pk_bf16_f32 v238, v104, v105
	v_cvt_pk_bf16_f32 v239, v106, v107
	v_mul_f32_e32 v182, v109, v109
	v_mul_f32_e32 v183, v111, v111
	v_fmac_f32_e32 v182, v108, v108
	v_fmac_f32_e32 v183, v110, v110
	v_add_f32_e32 v234, v182, v183
	v_mul_f32_e32 v182, v105, v105
	v_mul_f32_e32 v183, v107, v107
	v_fmac_f32_e32 v182, v104, v104
	v_fmac_f32_e32 v183, v106, v106
	v_add_f32_e32 v182, v182, v183
	v_add_f32_e32 v234, v234, v182
	v_permlane16_swap_b32_e32 v236, v238
	v_permlane16_swap_b32_e32 v237, v239
	global_store_dwordx4 v143, v[236:239], s[4:5] offset:0
	s_nop 1
	v_cvt_pk_bf16_f32 v236, v100, v101
	v_cvt_pk_bf16_f32 v237, v102, v103
	v_cvt_pk_bf16_f32 v238, v96, v97
	v_cvt_pk_bf16_f32 v239, v98, v99
	v_mul_f32_e32 v182, v101, v101
	v_mul_f32_e32 v183, v103, v103
	v_fmac_f32_e32 v182, v100, v100
	v_fmac_f32_e32 v183, v102, v102
	v_add_f32_e32 v182, v182, v183
	v_add_f32_e32 v234, v234, v182
	v_mul_f32_e32 v182, v97, v97
	v_mul_f32_e32 v183, v99, v99
	v_fmac_f32_e32 v182, v96, v96
	v_fmac_f32_e32 v183, v98, v98
	v_add_f32_e32 v182, v182, v183
	v_add_f32_e32 v234, v234, v182
	v_permlane16_swap_b32_e32 v236, v238
	v_permlane16_swap_b32_e32 v237, v239
	global_store_dwordx4 v143, v[236:239], s[4:5] offset:256
	v_mov_b32_e32 v235, v234
	s_nop 1
	v_permlane16_swap_b32_e32 v234, v235
	v_add_f32_e32 v234, v234, v235
	v_mov_b32_e32 v235, v234
	s_nop 1
	v_permlane32_swap_b32_e32 v234, v235
	v_add_f32_e32 v234, v234, v235
	s_add_u32 s4, s66, 0x800
	s_addc_u32 s5, s67, 0
	s_and_saveexec_b64 s[10:11], s[6:7]
	global_store_dword v142, v234, s[4:5]
	s_mov_b64 exec, s[10:11]
	s_add_u32 s4, s44, 0x120000
	s_addc_u32 s5, s45, 0
	global_load_dwordx4 v[218:221], v140, s[4:5] offset:0
	global_load_dwordx4 v[222:225], v140, s[4:5] offset:64
	global_load_dwordx4 v[226:229], v140, s[4:5] offset:512
	global_load_dwordx4 v[230:233], v140, s[4:5] offset:576
	s_waitcnt vmcnt(26)
	v_pk_add_f32 v[92:93], v[92:93], v[156:157]
	v_pk_add_f32 v[94:95], v[94:95], v[158:159]
	v_pk_add_f32 v[88:89], v[88:89], v[160:161]
	v_pk_add_f32 v[90:91], v[90:91], v[162:163]
	v_pk_add_f32 v[84:85], v[84:85], v[164:165]
	v_pk_add_f32 v[86:87], v[86:87], v[166:167]
	v_pk_add_f32 v[80:81], v[80:81], v[168:169]
	v_pk_add_f32 v[82:83], v[82:83], v[170:171]
	s_add_u32 s4, s46, 0x40000
	s_addc_u32 s5, s47, 0
	global_store_dwordx4 v140, v[92:95], s[4:5] offset:0
	global_store_dwordx4 v140, v[88:91], s[4:5] offset:64
	global_store_dwordx4 v140, v[84:87], s[4:5] offset:512
	global_store_dwordx4 v140, v[80:83], s[4:5] offset:576
	s_add_u32 s4, s48, 0x20000
	s_addc_u32 s5, s49, 0
	v_cvt_pk_bf16_f32 v236, v92, v93
	v_cvt_pk_bf16_f32 v237, v94, v95
	v_cvt_pk_bf16_f32 v238, v88, v89
	v_cvt_pk_bf16_f32 v239, v90, v91
	v_mul_f32_e32 v182, v93, v93
	v_mul_f32_e32 v183, v95, v95
	v_fmac_f32_e32 v182, v92, v92
	v_fmac_f32_e32 v183, v94, v94
	v_add_f32_e32 v234, v182, v183
	v_mul_f32_e32 v182, v89, v89
	v_mul_f32_e32 v183, v91, v91
	v_fmac_f32_e32 v182, v88, v88
	v_fmac_f32_e32 v183, v90, v90
	v_add_f32_e32 v182, v182, v183
	v_add_f32_e32 v234, v234, v182
	v_permlane16_swap_b32_e32 v236, v238
	v_permlane16_swap_b32_e32 v237, v239
	global_store_dwordx4 v143, v[236:239], s[4:5] offset:0
	s_nop 1
	v_cvt_pk_bf16_f32 v236, v84, v85
	v_cvt_pk_bf16_f32 v237, v86, v87
	v_cvt_pk_bf16_f32 v238, v80, v81
	v_cvt_pk_bf16_f32 v239, v82, v83
	v_mul_f32_e32 v182, v85, v85
	v_mul_f32_e32 v183, v87, v87
	v_fmac_f32_e32 v182, v84, v84
	v_fmac_f32_e32 v183, v86, v86
	v_add_f32_e32 v182, v182, v183
	v_add_f32_e32 v234, v234, v182
	v_mul_f32_e32 v182, v81, v81
	v_mul_f32_e32 v183, v83, v83
	v_fmac_f32_e32 v182, v80, v80
	v_fmac_f32_e32 v183, v82, v82
	v_add_f32_e32 v182, v182, v183
	v_add_f32_e32 v234, v234, v182
	v_permlane16_swap_b32_e32 v236, v238
	v_permlane16_swap_b32_e32 v237, v239
	global_store_dwordx4 v143, v[236:239], s[4:5] offset:256
	v_mov_b32_e32 v235, v234
	s_nop 1
	v_permlane16_swap_b32_e32 v234, v235
	v_add_f32_e32 v234, v234, v235
	v_mov_b32_e32 v235, v234
	s_nop 1
	v_permlane32_swap_b32_e32 v234, v235
	v_add_f32_e32 v234, v234, v235
	s_add_u32 s4, s66, 0x1000
	s_addc_u32 s5, s67, 0
	s_and_saveexec_b64 s[10:11], s[6:7]
	global_store_dword v142, v234, s[4:5]
	s_mov_b64 exec, s[10:11]
	s_add_u32 s4, s44, 0x140000
	s_addc_u32 s5, s45, 0
	global_load_dwordx4 v[156:159], v140, s[4:5] offset:0
	global_load_dwordx4 v[160:163], v140, s[4:5] offset:64
	global_load_dwordx4 v[164:167], v140, s[4:5] offset:512
	global_load_dwordx4 v[168:171], v140, s[4:5] offset:576
	s_waitcnt vmcnt(33)
; __device__ __forceinline__ unsigned cvt_pk_bf16(float lo, float hi) { unsigned r; asm volatile("v_cvt_pk_bf16_f32 %0, %1, %2" : "=v"(r) : "v"(lo), "v"(hi)); return r; }
;     __device__ __forceinline__ void operator()(const f32x4 (&acc)[2][2][4][2], const Unit& u, int wr, int wc, int fr, int fq) const {
;     ...
;             for (int m = 0; m < 4; ++m) { const int row = u.pm * BM + ai * HALF + wr * 64 + m * 16 + fr;
;                 const float* b = (row < HALF_TOK) ? base0 + (size_t)row * DM : base1 + (size_t)(row - HALF_TOK) * DM;
;                 float* o = out + (size_t)(row & omask) * DM; float sq = 0.f;
; #pragma unroll
;                 for (int bj = 0; bj < 2; ++bj)
; #pragma unroll
;                     for (int n = 0; n < 2; ++n) { const int c = col0 + bj * HALF + n * 16; const f32x4 bs = *(const f32x4*)(b + c); const f32x4 v = bs + acc[ai][bj][m][n]; *(f32x4*)(o + c) = v;
;                         if (xb) { sq += (v[0] * v[0] + v[1] * v[1]) + (v[2] * v[2] + v[3] * v[3]); *(u32x2*)(xb + (size_t)row * DM + c) = (u32x2){cvt_pk_bf16(v[0], v[1]), cvt_pk_bf16(v[2], v[3])}; } }
;                 if (xb) { sq += __shfl_xor(sq, 16); sq += __shfl_xor(sq, 32); if (fq == 0) ssq[(size_t)row * 32 + u.pn * 4 + wc] = sq; }
	v_pk_add_f32 v[76:77], v[76:77], v[144:145]
	v_pk_add_f32 v[78:79], v[78:79], v[146:147]
	v_pk_add_f32 v[72:73], v[72:73], v[148:149]
	v_pk_add_f32 v[74:75], v[74:75], v[150:151]
	v_pk_add_f32 v[68:69], v[68:69], v[172:173]
	v_pk_add_f32 v[70:71], v[70:71], v[174:175]
	v_pk_add_f32 v[64:65], v[64:65], v[176:177]
	v_pk_add_f32 v[66:67], v[66:67], v[178:179]
	s_add_u32 s4, s46, 0x60000
	s_addc_u32 s5, s47, 0
	global_store_dwordx4 v140, v[76:79], s[4:5] offset:0
	global_store_dwordx4 v140, v[72:75], s[4:5] offset:64
	global_store_dwordx4 v140, v[68:71], s[4:5] offset:512
	global_store_dwordx4 v140, v[64:67], s[4:5] offset:576
	s_add_u32 s4, s48, 0x30000
	s_addc_u32 s5, s49, 0
	v_cvt_pk_bf16_f32 v236, v76, v77
	v_cvt_pk_bf16_f32 v237, v78, v79
	v_cvt_pk_bf16_f32 v238, v72, v73
	v_cvt_pk_bf16_f32 v239, v74, v75
	v_mul_f32_e32 v182, v77, v77
	v_mul_f32_e32 v183, v79, v79
	v_fmac_f32_e32 v182, v76, v76
	v_fmac_f32_e32 v183, v78, v78
	v_add_f32_e32 v234, v182, v183
	v_mul_f32_e32 v182, v73, v73
	v_mul_f32_e32 v183, v75, v75
	v_fmac_f32_e32 v182, v72, v72
	v_fmac_f32_e32 v183, v74, v74
	v_add_f32_e32 v182, v182, v183
	v_add_f32_e32 v234, v234, v182
	v_permlane16_swap_b32_e32 v236, v238
	v_permlane16_swap_b32_e32 v237, v239
	global_store_dwordx4 v143, v[236:239], s[4:5] offset:0
	s_nop 1
	v_cvt_pk_bf16_f32 v236, v68, v69
	v_cvt_pk_bf16_f32 v237, v70, v71
	v_cvt_pk_bf16_f32 v238, v64, v65
	v_cvt_pk_bf16_f32 v239, v66, v67
	v_mul_f32_e32 v182, v69, v69
	v_mul_f32_e32 v183, v71, v71
	v_fmac_f32_e32 v182, v68, v68
	v_fmac_f32_e32 v183, v70, v70
	v_add_f32_e32 v182, v182, v183
	v_add_f32_e32 v234, v234, v182
	v_mul_f32_e32 v182, v65, v65
	v_mul_f32_e32 v183, v67, v67
	v_fmac_f32_e32 v182, v64, v64
	v_fmac_f32_e32 v183, v66, v66
	v_add_f32_e32 v182, v182, v183
	v_add_f32_e32 v234, v234, v182
	v_permlane16_swap_b32_e32 v236, v238
	v_permlane16_swap_b32_e32 v237, v239
	global_store_dwordx4 v143, v[236:239], s[4:5] offset:256
	v_mov_b32_e32 v235, v234
	s_nop 1
	v_permlane16_swap_b32_e32 v234, v235
	v_add_f32_e32 v234, v234, v235
	v_mov_b32_e32 v235, v234
	s_nop 1
	v_permlane32_swap_b32_e32 v234, v235
	v_add_f32_e32 v234, v234, v235
	s_add_u32 s4, s66, 0x1800
	s_addc_u32 s5, s67, 0
	s_and_saveexec_b64 s[10:11], s[6:7]
	global_store_dword v142, v234, s[4:5]
	s_mov_b64 exec, s[10:11]
	s_add_u32 s4, s44, 0x160000
	s_addc_u32 s5, s45, 0
	global_load_dwordx4 v[144:147], v140, s[4:5] offset:0
	global_load_dwordx4 v[148:151], v140, s[4:5] offset:64
	global_load_dwordx4 v[172:175], v140, s[4:5] offset:512
	global_load_dwordx4 v[176:179], v140, s[4:5] offset:576
	s_waitcnt vmcnt(33)
	v_pk_add_f32 v[60:61], v[60:61], v[202:203]
	v_pk_add_f32 v[62:63], v[62:63], v[204:205]
	v_pk_add_f32 v[56:57], v[56:57], v[206:207]
	v_pk_add_f32 v[58:59], v[58:59], v[208:209]
	v_pk_add_f32 v[52:53], v[52:53], v[210:211]
	v_pk_add_f32 v[54:55], v[54:55], v[212:213]
	v_pk_add_f32 v[48:49], v[48:49], v[214:215]
	v_pk_add_f32 v[50:51], v[50:51], v[216:217]
	s_add_u32 s4, s46, 0x100000
	s_addc_u32 s5, s47, 0
	global_store_dwordx4 v140, v[60:63], s[4:5] offset:0
	global_store_dwordx4 v140, v[56:59], s[4:5] offset:64
	global_store_dwordx4 v140, v[52:55], s[4:5] offset:512
	global_store_dwordx4 v140, v[48:51], s[4:5] offset:576
	s_add_u32 s4, s48, 0x80000
	s_addc_u32 s5, s49, 0
	v_cvt_pk_bf16_f32 v236, v60, v61
	v_cvt_pk_bf16_f32 v237, v62, v63
	v_cvt_pk_bf16_f32 v238, v56, v57
	v_cvt_pk_bf16_f32 v239, v58, v59
	v_mul_f32_e32 v182, v61, v61
	v_mul_f32_e32 v183, v63, v63
	v_fmac_f32_e32 v182, v60, v60
	v_fmac_f32_e32 v183, v62, v62
	v_add_f32_e32 v234, v182, v183
	v_mul_f32_e32 v182, v57, v57
	v_mul_f32_e32 v183, v59, v59
	v_fmac_f32_e32 v182, v56, v56
	v_fmac_f32_e32 v183, v58, v58
	v_add_f32_e32 v182, v182, v183
	v_add_f32_e32 v234, v234, v182
	v_permlane16_swap_b32_e32 v236, v238
	v_permlane16_swap_b32_e32 v237, v239
	global_store_dwordx4 v143, v[236:239], s[4:5] offset:0
	s_nop 1
	v_cvt_pk_bf16_f32 v236, v52, v53
	v_cvt_pk_bf16_f32 v237, v54, v55
	v_cvt_pk_bf16_f32 v238, v48, v49
	v_cvt_pk_bf16_f32 v239, v50, v51
	v_mul_f32_e32 v182, v53, v53
	v_mul_f32_e32 v183, v55, v55
	v_fmac_f32_e32 v182, v52, v52
	v_fmac_f32_e32 v183, v54, v54
	v_add_f32_e32 v182, v182, v183
	v_add_f32_e32 v234, v234, v182
	v_mul_f32_e32 v182, v49, v49
	v_mul_f32_e32 v183, v51, v51
	v_fmac_f32_e32 v182, v48, v48
	v_fmac_f32_e32 v183, v50, v50
	v_add_f32_e32 v182, v182, v183
	v_add_f32_e32 v234, v234, v182
	v_permlane16_swap_b32_e32 v236, v238
	v_permlane16_swap_b32_e32 v237, v239
	global_store_dwordx4 v143, v[236:239], s[4:5] offset:256
	v_mov_b32_e32 v235, v234
	s_nop 1
	v_permlane16_swap_b32_e32 v234, v235
	v_add_f32_e32 v234, v234, v235
	v_mov_b32_e32 v235, v234
	s_nop 1
	v_permlane32_swap_b32_e32 v234, v235
	v_add_f32_e32 v234, v234, v235
	s_add_u32 s4, s66, 0x4000
	s_addc_u32 s5, s67, 0
	s_and_saveexec_b64 s[10:11], s[6:7]
	global_store_dword v142, v234, s[4:5]
	s_mov_b64 exec, s[10:11]
	s_waitcnt vmcnt(29)
; __device__ __forceinline__ unsigned cvt_pk_bf16(float lo, float hi) { unsigned r; asm volatile("v_cvt_pk_bf16_f32 %0, %1, %2" : "=v"(r) : "v"(lo), "v"(hi)); return r; }
;     __device__ __forceinline__ void operator()(const f32x4 (&acc)[2][2][4][2], const Unit& u, int wr, int wc, int fr, int fq) const {
;     ...
;             for (int m = 0; m < 4; ++m) { const int row = u.pm * BM + ai * HALF + wr * 64 + m * 16 + fr;
;                 const float* b = (row < HALF_TOK) ? base0 + (size_t)row * DM : base1 + (size_t)(row - HALF_TOK) * DM;
;                 float* o = out + (size_t)(row & omask) * DM; float sq = 0.f;
; #pragma unroll
;                 for (int bj = 0; bj < 2; ++bj)
; #pragma unroll
;                     for (int n = 0; n < 2; ++n) { const int c = col0 + bj * HALF + n * 16; const f32x4 bs = *(const f32x4*)(b + c); const f32x4 v = bs + acc[ai][bj][m][n]; *(f32x4*)(o + c) = v;
;                         if (xb) { sq += (v[0] * v[0] + v[1] * v[1]) + (v[2] * v[2] + v[3] * v[3]); *(u32x2*)(xb + (size_t)row * DM + c) = (u32x2){cvt_pk_bf16(v[0], v[1]), cvt_pk_bf16(v[2], v[3])}; } }
;                 if (xb) { sq += __shfl_xor(sq, 16); sq += __shfl_xor(sq, 32); if (fq == 0) ssq[(size_t)row * 32 + u.pn * 4 + wc] = sq; }
	v_pk_add_f32 v[44:45], v[44:45], v[218:219]
	v_pk_add_f32 v[46:47], v[46:47], v[220:221]
	v_pk_add_f32 v[40:41], v[40:41], v[222:223]
	v_pk_add_f32 v[42:43], v[42:43], v[224:225]
	v_pk_add_f32 v[36:37], v[36:37], v[226:227]
	v_pk_add_f32 v[38:39], v[38:39], v[228:229]
	v_pk_add_f32 v[32:33], v[32:33], v[230:231]
	v_pk_add_f32 v[34:35], v[34:35], v[232:233]
	s_add_u32 s4, s46, 0x120000
	s_addc_u32 s5, s47, 0
	global_store_dwordx4 v140, v[44:47], s[4:5] offset:0
	global_store_dwordx4 v140, v[40:43], s[4:5] offset:64
	global_store_dwordx4 v140, v[36:39], s[4:5] offset:512
	global_store_dwordx4 v140, v[32:35], s[4:5] offset:576
	s_add_u32 s4, s48, 0x90000
	s_addc_u32 s5, s49, 0
	v_cvt_pk_bf16_f32 v236, v44, v45
	v_cvt_pk_bf16_f32 v237, v46, v47
	v_cvt_pk_bf16_f32 v238, v40, v41
	v_cvt_pk_bf16_f32 v239, v42, v43
	v_mul_f32_e32 v182, v45, v45
	v_mul_f32_e32 v183, v47, v47
	v_fmac_f32_e32 v182, v44, v44
	v_fmac_f32_e32 v183, v46, v46
	v_add_f32_e32 v234, v182, v183
	v_mul_f32_e32 v182, v41, v41
	v_mul_f32_e32 v183, v43, v43
	v_fmac_f32_e32 v182, v40, v40
	v_fmac_f32_e32 v183, v42, v42
	v_add_f32_e32 v182, v182, v183
	v_add_f32_e32 v234, v234, v182
	v_permlane16_swap_b32_e32 v236, v238
	v_permlane16_swap_b32_e32 v237, v239
	global_store_dwordx4 v143, v[236:239], s[4:5] offset:0
	s_nop 1
	v_cvt_pk_bf16_f32 v236, v36, v37
	v_cvt_pk_bf16_f32 v237, v38, v39
	v_cvt_pk_bf16_f32 v238, v32, v33
	v_cvt_pk_bf16_f32 v239, v34, v35
	v_mul_f32_e32 v182, v37, v37
	v_mul_f32_e32 v183, v39, v39
	v_fmac_f32_e32 v182, v36, v36
	v_fmac_f32_e32 v183, v38, v38
	v_add_f32_e32 v182, v182, v183
	v_add_f32_e32 v234, v234, v182
	v_mul_f32_e32 v182, v33, v33
	v_mul_f32_e32 v183, v35, v35
	v_fmac_f32_e32 v182, v32, v32
	v_fmac_f32_e32 v183, v34, v34
	v_add_f32_e32 v182, v182, v183
	v_add_f32_e32 v234, v234, v182
	v_permlane16_swap_b32_e32 v236, v238
	v_permlane16_swap_b32_e32 v237, v239
	global_store_dwordx4 v143, v[236:239], s[4:5] offset:256
	v_mov_b32_e32 v235, v234
	s_nop 1
	v_permlane16_swap_b32_e32 v234, v235
	v_add_f32_e32 v234, v234, v235
	v_mov_b32_e32 v235, v234
	s_nop 1
	v_permlane32_swap_b32_e32 v234, v235
	v_add_f32_e32 v234, v234, v235
	s_add_u32 s4, s66, 0x4800
	s_addc_u32 s5, s67, 0
	s_and_saveexec_b64 s[10:11], s[6:7]
	global_store_dword v142, v234, s[4:5]
	s_mov_b64 exec, s[10:11]
	s_waitcnt vmcnt(25)
	v_pk_add_f32 v[28:29], v[28:29], v[156:157]
	v_pk_add_f32 v[30:31], v[30:31], v[158:159]
	v_pk_add_f32 v[24:25], v[24:25], v[160:161]
	v_pk_add_f32 v[26:27], v[26:27], v[162:163]
	v_pk_add_f32 v[20:21], v[20:21], v[164:165]
	v_pk_add_f32 v[22:23], v[22:23], v[166:167]
	v_pk_add_f32 v[16:17], v[16:17], v[168:169]
	v_pk_add_f32 v[18:19], v[18:19], v[170:171]
	s_add_u32 s4, s46, 0x140000
	s_addc_u32 s5, s47, 0
	global_store_dwordx4 v140, v[28:31], s[4:5] offset:0
	global_store_dwordx4 v140, v[24:27], s[4:5] offset:64
	global_store_dwordx4 v140, v[20:23], s[4:5] offset:512
	global_store_dwordx4 v140, v[16:19], s[4:5] offset:576
	s_add_u32 s4, s48, 0xa0000
	s_addc_u32 s5, s49, 0
	v_cvt_pk_bf16_f32 v236, v28, v29
	v_cvt_pk_bf16_f32 v237, v30, v31
	v_cvt_pk_bf16_f32 v238, v24, v25
	v_cvt_pk_bf16_f32 v239, v26, v27
	v_mul_f32_e32 v182, v29, v29
	v_mul_f32_e32 v183, v31, v31
	v_fmac_f32_e32 v182, v28, v28
	v_fmac_f32_e32 v183, v30, v30
	v_add_f32_e32 v234, v182, v183
	v_mul_f32_e32 v182, v25, v25
	v_mul_f32_e32 v183, v27, v27
	v_fmac_f32_e32 v182, v24, v24
	v_fmac_f32_e32 v183, v26, v26
	v_add_f32_e32 v182, v182, v183
	v_add_f32_e32 v234, v234, v182
	v_permlane16_swap_b32_e32 v236, v238
	v_permlane16_swap_b32_e32 v237, v239
	global_store_dwordx4 v143, v[236:239], s[4:5] offset:0
	s_nop 1
	v_cvt_pk_bf16_f32 v236, v20, v21
	v_cvt_pk_bf16_f32 v237, v22, v23
	v_cvt_pk_bf16_f32 v238, v16, v17
	v_cvt_pk_bf16_f32 v239, v18, v19
	v_mul_f32_e32 v182, v21, v21
	v_mul_f32_e32 v183, v23, v23
	v_fmac_f32_e32 v182, v20, v20
	v_fmac_f32_e32 v183, v22, v22
	v_add_f32_e32 v182, v182, v183
	v_add_f32_e32 v234, v234, v182
	v_mul_f32_e32 v182, v17, v17
	v_mul_f32_e32 v183, v19, v19
	v_fmac_f32_e32 v182, v16, v16
	v_fmac_f32_e32 v183, v18, v18
	v_add_f32_e32 v182, v182, v183
	v_add_f32_e32 v234, v234, v182
	v_permlane16_swap_b32_e32 v236, v238
	v_permlane16_swap_b32_e32 v237, v239
	global_store_dwordx4 v143, v[236:239], s[4:5] offset:256
	v_mov_b32_e32 v235, v234
	s_nop 1
	v_permlane16_swap_b32_e32 v234, v235
	v_add_f32_e32 v234, v234, v235
	v_mov_b32_e32 v235, v234
	s_nop 1
	v_permlane32_swap_b32_e32 v234, v235
	v_add_f32_e32 v234, v234, v235
	s_add_u32 s4, s66, 0x5000
	s_addc_u32 s5, s67, 0
	s_and_saveexec_b64 s[10:11], s[6:7]
	global_store_dword v142, v234, s[4:5]
	s_mov_b64 exec, s[10:11]
	s_waitcnt vmcnt(21)
	v_pk_add_f32 v[12:13], v[12:13], v[144:145]
	v_pk_add_f32 v[14:15], v[14:15], v[146:147]
	v_pk_add_f32 v[8:9], v[8:9], v[148:149]
	v_pk_add_f32 v[10:11], v[10:11], v[150:151]
	v_pk_add_f32 v[4:5], v[4:5], v[172:173]
	v_pk_add_f32 v[6:7], v[6:7], v[174:175]
	v_pk_add_f32 v[0:1], v[0:1], v[176:177]
	v_pk_add_f32 v[2:3], v[2:3], v[178:179]
	s_add_u32 s4, s46, 0x160000
	s_addc_u32 s5, s47, 0
	global_store_dwordx4 v140, v[12:15], s[4:5] offset:0
	global_store_dwordx4 v140, v[8:11], s[4:5] offset:64
	global_store_dwordx4 v140, v[4:7], s[4:5] offset:512
	global_store_dwordx4 v140, v[0:3], s[4:5] offset:576
	s_add_u32 s4, s48, 0xb0000
	s_addc_u32 s5, s49, 0
	v_cvt_pk_bf16_f32 v236, v12, v13
	v_cvt_pk_bf16_f32 v237, v14, v15
	v_cvt_pk_bf16_f32 v238, v8, v9
	v_cvt_pk_bf16_f32 v239, v10, v11
	v_mul_f32_e32 v182, v13, v13
	v_mul_f32_e32 v183, v15, v15
	v_fmac_f32_e32 v182, v12, v12
	v_fmac_f32_e32 v183, v14, v14
	v_add_f32_e32 v234, v182, v183
	v_mul_f32_e32 v182, v9, v9
	v_mul_f32_e32 v183, v11, v11
	v_fmac_f32_e32 v182, v8, v8
	v_fmac_f32_e32 v183, v10, v10
	v_add_f32_e32 v182, v182, v183
	v_add_f32_e32 v234, v234, v182
	v_permlane16_swap_b32_e32 v236, v238
	v_permlane16_swap_b32_e32 v237, v239
	global_store_dwordx4 v143, v[236:239], s[4:5] offset:0
	s_nop 1
	v_cvt_pk_bf16_f32 v236, v4, v5
	v_cvt_pk_bf16_f32 v237, v6, v7
	v_cvt_pk_bf16_f32 v238, v0, v1
	v_cvt_pk_bf16_f32 v239, v2, v3
	v_mul_f32_e32 v182, v5, v5
	v_mul_f32_e32 v183, v7, v7
	v_fmac_f32_e32 v182, v4, v4
	v_fmac_f32_e32 v183, v6, v6
	v_add_f32_e32 v182, v182, v183
	v_add_f32_e32 v234, v234, v182
	v_mul_f32_e32 v182, v1, v1
	v_mul_f32_e32 v183, v3, v3
	v_fmac_f32_e32 v182, v0, v0
	v_fmac_f32_e32 v183, v2, v2
	v_add_f32_e32 v182, v182, v183
	v_add_f32_e32 v234, v234, v182
	v_permlane16_swap_b32_e32 v236, v238
	v_permlane16_swap_b32_e32 v237, v239
	global_store_dwordx4 v143, v[236:239], s[4:5] offset:256
	v_mov_b32_e32 v235, v234
	s_nop 1
	v_permlane16_swap_b32_e32 v234, v235
	v_add_f32_e32 v234, v234, v235
	v_mov_b32_e32 v235, v234
	s_nop 1
	v_permlane32_swap_b32_e32 v234, v235
	v_add_f32_e32 v234, v234, v235
	s_add_u32 s4, s66, 0x5800
	s_addc_u32 s5, s67, 0
	s_and_saveexec_b64 s[10:11], s[6:7]
	global_store_dword v142, v234, s[4:5]
	s_mov_b64 exec, s[10:11]
	s_branch .Lepi_done
